# P2 dilated-attention items rebalanced: the 64 workgroups without a q-up GEMM unit take 9 items, the other 192 take 5 (was 6 each)
# speedup vs baseline: 1.0092x; 1.0092x over previous
; DI PP getpp() { PP pp = (PP)__builtin_amdgcn_kernarg_segment_ptr(); asm volatile("" : "+s"(pp)); return pp; }
; __global__ void __launch_bounds__(512, 2) hymba_fwd(Params p_unused) {
;     ...
;         { PP p = getpp(); unsigned char* ws = p->ws;
;           AttnPtrs AP{ws, l};
;           for (int it = blockIdx.x; it < 1536; it += gridDim.x) {
;               const int pat = it >> 9, b = (it >> 7) & 3, hd = (it >> 4) & 7, x = it & 15;
;               const int dmul = pat == 0 ? 1 : (pat == 1 ? 4 : 16), nper = 16 / dmul, r0 = x / nper, nbk = x % nper;
.LBB0_869:
	v_readlane_b32 s0, v253, 55
	v_readlane_b32 s6, v253, 3
	v_readlane_b32 s1, v253, 56
	v_readlane_b32 s7, v253, 4
	s_and_b64 vcc, exec, s[0:1]
	s_waitcnt lgkmcnt(0)
	s_barrier
	s_cbranch_vccz .LBB0_885
	s_load_dwordx2 s[6:7], s[6:7], 0xd8
	s_mov_b32 s18, s2
	s_mov_b32 s100, 0
	s_waitcnt lgkmcnt(0)
	s_add_u32 s8, s6, 0x1eb00000
	s_addc_u32 s9, s7, 0
	s_add_u32 s10, s6, 0x1fb00000
	s_addc_u32 s11, s7, 0
	s_add_u32 s12, s6, 0x1f300000
	s_addc_u32 s13, s7, 0
	s_add_u32 s0, s6, 0x23b00000
	s_addc_u32 s1, s7, 0
	s_add_u32 s16, s6, 0x26b00000
	s_addc_u32 s17, s7, 0
	s_branch .LBB0_873

; __global__ void __launch_bounds__(512, 2) hymba_fwd(Params p_unused) {
;     ...
;           for (int it = blockIdx.x; it < 1536; it += gridDim.x) {
;               const int pat = it >> 9, b = (it >> 7) & 3, hd = (it >> 4) & 7, x = it & 15;
;               const int dmul = pat == 0 ? 1 : (pat == 1 ? 4 : 16), nper = 16 / dmul, r0 = x / nper, nbk = x % nper;
;     ...
;               attn_unit<1>(lds, AP, b, hd, nbk * 128, dmul, r0, pat, nbk > 0 ? nbk - 1 : 0, nbk + 1);
;               if (DUP_MIX & 1) attn_unit<1>(lds, AP, b, hd, nbk * 128, dmul, r0, pat, nbk > 0 ? nbk - 1 : 0, nbk + 1);
;     ...
;           }
.LBB0_872:
	s_cmp_lg_u32 s26, 0x100
	s_cbranch_scc1 .Ldil_orig
	s_cmp_lt_u32 s2, 0xc0
	s_cbranch_scc0 .Ldil_hi
	s_add_i32 s18, s18, s26
	s_cmpk_gt_i32 s18, 0x4ff
	s_cbranch_scc1 .LBB0_885
	s_branch .LBB0_873
.Ldil_hi:
	s_cmp_lg_u32 s100, 0
	s_cbranch_scc1 .Ldil_extra
	s_add_i32 s18, s18, s26
	s_cmpk_gt_i32 s18, 0x5ff
	s_cbranch_scc0 .LBB0_873
	s_sub_i32 s101, s2, 0xc0
	s_mul_i32 s101, s101, 3
	s_add_i32 s101, s101, 0x500
	s_mov_b32 s18, s101
	s_mov_b32 s100, 1
	s_branch .LBB0_873
.Ldil_extra:
	s_add_i32 s100, s100, 1
	s_cmp_gt_u32 s100, 3
	s_cbranch_scc1 .LBB0_885
	s_add_i32 s18, s101, s100
	s_add_i32 s18, s18, -1
	s_branch .LBB0_873
